# C1 with write-through (sc1) stores of the residual stream x in the two norm phases
# baseline (speedup 1.0000x reference)
; __device__ __forceinline__ unsigned pk2(float lo, float hi) { const hwf2 v = {lo, hi}; return __builtin_bit_cast(unsigned, __builtin_convertvector(v, hwbf2)); }
; __device__ __forceinline__ void ph_norm(const bf16_t* xin, const bf16_t* h, float scale, const float* ga, bf16_t* xout16, float* xout32, float* rsq) {
;     ...
;         if (xout16) { u32x4* xo = (u32x4*)(xout16 + XB_OFF(row, lane));
; #pragma unroll
;             for (int jx = 0; jx < 4; ++jx) xo[XB_JSTEP * jx] = (u32x4){pk2(xv[8 * jx], xv[8 * jx + 1]), pk2(xv[8 * jx + 2], xv[8 * jx + 3]), pk2(xv[8 * jx + 4], xv[8 * jx + 5]), pk2(xv[8 * jx + 6], xv[8 * jx + 7])}; }
;         if (xout32) { f32x4* xo = (f32x4*)(xout32 + (size_t)row * DM) + 2 * lane;
; #pragma unroll
;             for (int jx = 0; jx < 4; ++jx) { xo[128 * jx] = (f32x4){xv[8 * jx], xv[8 * jx + 1], xv[8 * jx + 2], xv[8 * jx + 3]}; xo[128 * jx + 1] = (f32x4){xv[8 * jx + 4], xv[8 * jx + 5], xv[8 * jx + 6], xv[8 * jx + 7]}; } }
;     }
.LBB0_680:
	v_ashrrev_i32_e32 v36, 8, v108
	v_ashrrev_i32_e32 v37, 31, v36
	v_lshlrev_b64 v[36:37], 13, v[36:37]
	s_movk_i32 s11, 0xff
	v_and_or_b32 v36, v108, s11, v36
	v_or_b32_e32 v36, v36, v104
	v_lshlrev_b64 v[36:37], 7, v[36:37]
	v_lshl_add_u64 v[36:37], v[110:111], 0, v[36:37]
	s_mov_b32 s11, 0x40000
	v_cvt_pk_bf16_f32 v122, v100, v101
	s_waitcnt lgkmcnt(0)
	v_cvt_pk_bf16_f32 v123, v102, v103
	v_cvt_pk_bf16_f32 v124, v96, v97
	v_cvt_pk_bf16_f32 v125, v98, v99
	v_add_co_u32_e32 v38, vcc, s11, v36
	global_store_dwordx4 v[36:37], v[122:125], off sc1
	s_nop 0
	v_addc_co_u32_e32 v39, vcc, 0, v37, vcc
	v_cvt_pk_bf16_f32 v122, v92, v93
	v_cvt_pk_bf16_f32 v123, v94, v95
	v_cvt_pk_bf16_f32 v124, v88, v89
	v_cvt_pk_bf16_f32 v125, v90, v91
	s_mov_b32 s11, 0x80000
	global_store_dwordx4 v[38:39], v[122:125], off sc1
	v_add_co_u32_e32 v38, vcc, s11, v36
	s_nop 0
	v_cvt_pk_bf16_f32 v122, v84, v85
	v_addc_co_u32_e32 v39, vcc, 0, v37, vcc
	v_cvt_pk_bf16_f32 v123, v86, v87
	v_cvt_pk_bf16_f32 v124, v80, v81
	v_cvt_pk_bf16_f32 v125, v82, v83
	v_add_co_u32_e32 v36, vcc, 0xc0000, v36
	global_store_dwordx4 v[38:39], v[122:125], off sc1
	s_nop 0
	v_addc_co_u32_e32 v37, vcc, 0, v37, vcc
	v_cvt_pk_bf16_f32 v122, v76, v77
	v_cvt_pk_bf16_f32 v123, v78, v79
	v_cvt_pk_bf16_f32 v124, v72, v73
	v_cvt_pk_bf16_f32 v125, v74, v75
	global_store_dwordx4 v[36:37], v[122:125], off sc1
	s_andn2_b64 vcc, exec, s[16:17]
	s_cbranch_vccnz .LBB0_673

; __device__ __forceinline__ unsigned pk2(float lo, float hi) { const hwf2 v = {lo, hi}; return __builtin_bit_cast(unsigned, __builtin_convertvector(v, hwbf2)); }
; __device__ __forceinline__ void ph_norm(const bf16_t* xin, const bf16_t* h, float scale, const float* ga, bf16_t* xout16, float* xout32, float* rsq) {
;     ...
;     for (int row = gw; row < M; row += NGW) {
;         u32x4 xw[4], hw[4];
; #pragma unroll
;         for (int jx = 0; jx < 4; ++jx) { xw[jx] = xn[jx]; hw[jx] = hn[jx]; }
;         const int nrow = row + NGW;
;         if (nrow < M) { const u32x4* xr = (const u32x4*)(xin + XB_OFF(nrow, lane)); const u32x4* hr = (const u32x4*)(h + (size_t)nrow * DM) + lane;
; #pragma unroll
;             for (int jx = 0; jx < 4; ++jx) { xn[jx] = xr[XB_JSTEP * jx]; hn[jx] = __builtin_nontemporal_load(hr + 64 * jx); } }
;     ...
;         if (xout16) { u32x4* xo = (u32x4*)(xout16 + XB_OFF(row, lane));
; #pragma unroll
;             for (int jx = 0; jx < 4; ++jx) xo[XB_JSTEP * jx] = (u32x4){pk2(xv[8 * jx], xv[8 * jx + 1]), pk2(xv[8 * jx + 2], xv[8 * jx + 3]), pk2(xv[8 * jx + 4], xv[8 * jx + 5]), pk2(xv[8 * jx + 6], xv[8 * jx + 7])}; }
.LBB0_2341:
	s_or_b64 exec, exec, s[18:19]
	v_ashrrev_i32_e32 v36, 8, v106
	s_and_b64 s[0:1], exec, s[0:1]
	v_ashrrev_i32_e32 v37, 31, v36
	s_or_b64 s[16:17], s[0:1], s[16:17]
	v_lshlrev_b64 v[36:37], 13, v[36:37]
	s_movk_i32 s0, 0xff
	v_and_or_b32 v36, v106, s0, v36
	v_or_b32_e32 v36, v36, v104
	v_lshlrev_b64 v[36:37], 7, v[36:37]
	s_waitcnt lgkmcnt(0)
	v_lshl_add_u64 v[118:119], v[108:109], 0, v[36:37]
	v_cvt_pk_bf16_f32 v36, v90, v91
	v_cvt_pk_bf16_f32 v37, v94, v95
	v_cvt_pk_bf16_f32 v38, v98, v99
	v_cvt_pk_bf16_f32 v39, v102, v103
	s_mov_b32 s0, 0x40000
	global_store_dwordx4 v[118:119], v[36:39], off sc1
	v_lshl_add_u64 v[110:111], v[110:111], 0, s[8:9]
	v_lshl_add_u64 v[112:113], v[112:113], 0, s[10:11]
	v_cvt_pk_bf16_f32 v36, v88, v89
	v_add_co_u32_e32 v88, vcc, s0, v118
	v_cvt_pk_bf16_f32 v37, v92, v93
	v_cvt_pk_bf16_f32 v38, v96, v97
	v_cvt_pk_bf16_f32 v39, v100, v101
	v_addc_co_u32_e32 v89, vcc, 0, v119, vcc
	s_mov_b32 s0, 0x80000
	global_store_dwordx4 v[88:89], v[36:39], off sc1
	s_waitcnt vmcnt(8)
	v_mov_b64_e32 v[102:103], v[42:43]
	s_waitcnt vmcnt(7)
	v_mov_b64_e32 v[94:95], v[50:51]
	v_cvt_pk_bf16_f32 v36, v80, v81
	v_add_co_u32_e32 v80, vcc, s0, v118
	v_cvt_pk_bf16_f32 v37, v82, v83
	v_cvt_pk_bf16_f32 v38, v84, v85
	v_cvt_pk_bf16_f32 v39, v86, v87
	v_addc_co_u32_e32 v81, vcc, 0, v119, vcc
	global_store_dwordx4 v[80:81], v[36:39], off sc1
	s_waitcnt vmcnt(7)
	v_mov_b64_e32 v[90:91], v[58:59]
	s_waitcnt vmcnt(3)
	v_mov_b64_e32 v[86:87], v[66:67]
	v_cvt_pk_bf16_f32 v36, v52, v53
	v_add_co_u32_e32 v52, vcc, 0xc0000, v118
	v_cvt_pk_bf16_f32 v37, v76, v77
	v_cvt_pk_bf16_f32 v38, v78, v79
	v_cvt_pk_bf16_f32 v39, v54, v55
	v_addc_co_u32_e32 v53, vcc, 0, v119, vcc
	global_store_dwordx4 v[52:53], v[36:39], off sc1
	v_mov_b64_e32 v[98:99], v[46:47]
	v_mov_b64_e32 v[82:83], v[70:71]
	v_mov_b64_e32 v[78:79], v[62:63]
	v_mov_b64_e32 v[52:53], v[72:73]
	v_mov_b64_e32 v[100:101], v[40:41]
	v_mov_b64_e32 v[92:93], v[48:49]
	v_mov_b64_e32 v[88:89], v[56:57]
	v_mov_b64_e32 v[84:85], v[64:65]
	v_mov_b64_e32 v[96:97], v[44:45]
	v_mov_b64_e32 v[80:81], v[68:69]
	v_mov_b64_e32 v[76:77], v[60:61]
	v_mov_b64_e32 v[54:55], v[74:75]
	v_mov_b32_e32 v106, v107
	s_andn2_b64 exec, exec, s[16:17]
	s_cbranch_execz .LBB0_2346
